# P8: row scale/sum pairs gathered in LDS and written as two 256-byte stores per workgroup instead of 128 four-byte write-through stores
# baseline (speedup 1.0000x reference)
; __device__ __forceinline__ void xn2_rows(const bf16* __restrict__ hb, const float* __restrict__ g, bf16* __restrict__ outp, unsigned char* __restrict__ xq, float* __restrict__ xs, int gwave, int nwaves, int lane, int rend) {
;     const __amdgpu_buffer_rsrc_t rsO = __builtin_amdgcn_make_buffer_rsrc((void*)outp, 0, (unsigned)T * D * 2u, 0x00020000), rsQ = __builtin_amdgcn_make_buffer_rsrc((void*)xq, 0, 16u * (unsigned)MiB, 0x00020000);
; #pragma unroll 2
;     for (int row = gwave; row < rend; row += nwaves) {
;         const v4u* xb = (const v4u*)(hb + (size_t)row * D) + lane;
;         float v[2][8]; float ss = 0.f;
; #pragma unroll
;         for (int j = 0; j < 2; ++j) { const v4u w = xb[64 * j]; const unsigned ww[4] = {w.x, w.y, w.z, w.w};
; #pragma unroll
;             for (int e = 0; e < 4; ++e) { v[j][2 * e] = __uint_as_float(ww[e] << 16); v[j][2 * e + 1] = __uint_as_float(ww[e] & 0xffff0000u); ss += v[j][2 * e] * v[j][2 * e] + v[j][2 * e + 1] * v[j][2 * e + 1]; } }
;         ss = wave_sum(ss);
;         const float r = rsqrtf(ss * (1.f / D) + EPS);
;         float y[2][8]; float mx = 0.f;
; #pragma unroll
;         for (int j = 0; j < 2; ++j) { const float4 g0 = ((const float4*)g)[2 * lane + 128 * j], g1 = ((const float4*)g)[2 * lane + 128 * j + 1]; const float gg[8] = {g0.x, g0.y, g0.z, g0.w, g1.x, g1.y, g1.z, g1.w};
; #pragma unroll
;             for (int e = 0; e < 8; ++e) { y[j][e] = v[j][e] * r * gg[e]; mx = fmaxf(mx, fabsf(y[j][e])); }
;             v4u ow; ow.x = pk2(y[j][0], y[j][1]); ow.y = pk2(y[j][2], y[j][3]); ow.z = pk2(y[j][4], y[j][5]); ow.w = pk2(y[j][6], y[j][7]);
;             __builtin_amdgcn_raw_buffer_store_b128(ow, rsO, (int)(((unsigned)row * D + 8u * (unsigned)lane + 512u * j) * 2u), 0, 16); }
;         mx = wave_max_dpp(mx);
;         const float sc = mx > 0.f ? mx * (1.f / 119.f) : 1.f, inv = 1.f / sc;
.LBB0_564:
	s_or_b64 exec, exec, s[10:11]
	s_andn2_b64 vcc, exec, s[20:21]
	s_barrier
	s_cbranch_vccnz .LBB0_569
	global_load_dwordx4 v[2:5], v[20:21], off offset:16
	global_load_dwordx4 v[6:9], v[20:21], off
	global_load_dwordx4 v[10:13], v[20:21], off offset:2064
	global_load_dwordx4 v[14:17], v[20:21], off offset:2048
	s_lshl_b32 s10, s42, 6
	s_lshl_b32 s11, s43, 8
	s_add_i32 s24, s10, s11
	s_add_i32 s24, s24, s95
	s_ashr_i32 s25, s24, 31
	s_lshl_b64 s[10:11], s[24:25], 2
	s_lshl_b32 s98, s95, 2
	v_lshl_add_u32 v33, s24, 9, v1
	s_lshl_b64 s[24:25], s[24:25], 11
	v_mov_b32_e32 v27, s25
	v_or_b32_e32 v26, s24, v18
	v_lshl_add_u64 v[148:149], s[90:91], 0, v[26:27]
	s_mov_b32 s24, 0xa400000
	s_mov_b32 s25, 0
	s_nop 0
	v_lshl_add_u64 v[148:149], v[148:149], 0, s[24:25]
	v_lshl_add_u64 v[150:151], v[148:149], 0, s[22:23]
	global_load_dwordx4 v[84:87], v[148:149], off
	global_load_dwordx4 v[88:91], v[148:149], off offset:1024
	global_load_dwordx4 v[92:95], v[150:151], off
	global_load_dwordx4 v[96:99], v[150:151], off offset:1024
	s_mov_b32 s46, 0x4b400008
	s_mov_b32 s47, 0x4b400008
	s_mov_b32 s48, 0x0c0c0400
	s_mov_b32 s49, 0x05040100
	s_mov_b32 s45, 0x0f0f0f0f
	s_mov_b32 s100, 0x8000
	s_mov_b32 s101, 0
	s_mov_b32 s32, 0
	v_mov_b32_e32 v55, 0
	v_mov_b32_e32 v61, 0
	v_mov_b32_e32 v210, v26
	v_mov_b32_e32 v211, v33
	s_waitcnt vmcnt(0)
.Lp8_trip:
	s_waitcnt vmcnt(8)
	v_lshlrev_b32_e32 v34, 16, v84
	v_and_b32_e32 v35, 0xffff0000, v84
	v_lshlrev_b32_e32 v36, 16, v85
	v_and_b32_e32 v37, 0xffff0000, v85
	v_lshlrev_b32_e32 v38, 16, v86
	v_and_b32_e32 v39, 0xffff0000, v86
	v_lshlrev_b32_e32 v40, 16, v87
	v_and_b32_e32 v41, 0xffff0000, v87
	v_lshlrev_b32_e32 v42, 16, v88
	v_and_b32_e32 v43, 0xffff0000, v88
	v_lshlrev_b32_e32 v44, 16, v89
	v_and_b32_e32 v45, 0xffff0000, v89
	v_lshlrev_b32_e32 v46, 16, v90
	v_and_b32_e32 v47, 0xffff0000, v90
	v_lshlrev_b32_e32 v48, 16, v91
	v_and_b32_e32 v49, 0xffff0000, v91
	v_lshl_add_u64 v[148:149], v[148:149], 0, s[100:101]
	global_load_dwordx4 v[84:87], v[148:149], off
	global_load_dwordx4 v[88:91], v[148:149], off offset:1024
	v_pk_mul_f32 v[50:51], v[34:35], v[34:35]
	v_pk_fma_f32 v[50:51], v[36:37], v[36:37], v[50:51]
	v_pk_fma_f32 v[50:51], v[38:39], v[38:39], v[50:51]
	v_pk_fma_f32 v[50:51], v[40:41], v[40:41], v[50:51]
	v_pk_fma_f32 v[50:51], v[42:43], v[42:43], v[50:51]
	v_pk_fma_f32 v[50:51], v[44:45], v[44:45], v[50:51]
	v_pk_fma_f32 v[50:51], v[46:47], v[46:47], v[50:51]
	v_pk_fma_f32 v[50:51], v[48:49], v[48:49], v[50:51]
	v_add_f32_e32 v52, v50, v51
	s_nop 1
	v_add_f32_dpp v52, v52, v52 quad_perm:[1,0,3,2] row_mask:0xf bank_mask:0xf bound_ctrl:1
	s_nop 1
	v_add_f32_dpp v52, v52, v52 quad_perm:[2,3,0,1] row_mask:0xf bank_mask:0xf bound_ctrl:1
	s_nop 1
	v_add_f32_dpp v52, v52, v52 row_half_mirror row_mask:0xf bank_mask:0xf bound_ctrl:1
	s_nop 1
	v_add_f32_dpp v52, v52, v52 row_mirror row_mask:0xf bank_mask:0xf bound_ctrl:1
	s_nop 1
	v_readlane_b32 s28, v52, 16
	v_readlane_b32 s29, v52, 48
	v_readlane_b32 s24, v52, 0
	v_readlane_b32 s25, v52, 32
	s_nop 1
	v_mov_b32_e32 v52, s28
	v_mov_b32_e32 v53, s29
	v_pk_add_f32 v[52:53], s[24:25], v[52:53]
	s_nop 0
	v_add_f32_e32 v52, v52, v53
	v_fmamk_f32 v52, v52, 0x3a800000, v29
	v_rsq_f32_e32 v54, v52
	s_nop 0
	v_pk_mul_f32 v[56:57], v[54:55], v[34:35] op_sel_hi:[0,1]
	v_pk_mul_f32 v[164:165], v[6:7], v[56:57]
	v_pk_mul_f32 v[56:57], v[54:55], v[36:37] op_sel_hi:[0,1]
	v_pk_mul_f32 v[166:167], v[8:9], v[56:57]
	v_pk_mul_f32 v[56:57], v[54:55], v[38:39] op_sel_hi:[0,1]
	v_pk_mul_f32 v[168:169], v[2:3], v[56:57]
	v_pk_mul_f32 v[56:57], v[54:55], v[40:41] op_sel_hi:[0,1]
	v_pk_mul_f32 v[170:171], v[4:5], v[56:57]
	v_pk_mul_f32 v[56:57], v[54:55], v[42:43] op_sel_hi:[0,1]
	v_pk_mul_f32 v[172:173], v[14:15], v[56:57]
	v_pk_mul_f32 v[56:57], v[54:55], v[44:45] op_sel_hi:[0,1]
	v_pk_mul_f32 v[174:175], v[16:17], v[56:57]
	v_pk_mul_f32 v[56:57], v[54:55], v[46:47] op_sel_hi:[0,1]
	v_pk_mul_f32 v[176:177], v[10:11], v[56:57]
	v_pk_mul_f32 v[56:57], v[54:55], v[48:49] op_sel_hi:[0,1]
	v_pk_mul_f32 v[178:179], v[12:13], v[56:57]
	v_max3_f32 v58, |v164|, 0, |v165|
	v_max3_f32 v58, v58, |v166|, |v167|
	v_max3_f32 v58, v58, |v168|, |v169|
	v_max3_f32 v58, v58, |v170|, |v171|
	v_max3_f32 v58, v58, |v172|, |v173|
	v_max3_f32 v58, v58, |v174|, |v175|
	v_max3_f32 v58, v58, |v176|, |v177|
	v_max3_f32 v58, v58, |v178|, |v179|
	v_cvt_pk_bf16_f32 v62, v164, v165
	v_cvt_pk_bf16_f32 v63, v166, v167
	v_cvt_pk_bf16_f32 v64, v168, v169
	v_cvt_pk_bf16_f32 v65, v170, v171
	v_cvt_pk_bf16_f32 v66, v172, v173
	v_cvt_pk_bf16_f32 v67, v174, v175
	v_cvt_pk_bf16_f32 v68, v176, v177
	v_cvt_pk_bf16_f32 v69, v178, v179
	buffer_store_dwordx4 v[62:65], v210, s[12:15], 0 offen sc1
	buffer_store_dwordx4 v[66:69], v210, s[12:15], 0 offen offset:1024 sc1
	v_add_u32_e32 v210, 0x4000, v210
	s_nop 1
	v_max_f32_dpp v58, v58, v58 quad_perm:[1,0,3,2] row_mask:0xf bank_mask:0xf
	s_nop 1
	v_max_f32_dpp v58, v58, v58 quad_perm:[2,3,0,1] row_mask:0xf bank_mask:0xf
	s_nop 1
	v_max_f32_dpp v58, v58, v58 row_half_mirror row_mask:0xf bank_mask:0xf
	s_nop 1
	v_max_f32_dpp v58, v58, v58 row_mirror row_mask:0xf bank_mask:0xf
	s_nop 1
	v_readlane_b32 s28, v58, 32
	v_readlane_b32 s29, v58, 48
	v_readlane_b32 s24, v58, 0
	v_readlane_b32 s25, v58, 16
	s_nop 1
	v_mov_b32_e32 v59, s29
	v_max_f32_e32 v59, s28, v59
	v_mov_b32_e32 v70, s25
	v_max3_f32 v59, s24, v70, v59
	v_mul_f32_e32 v70, 0x3c09ae41, v59
	v_cmp_lt_f32_e32 vcc, 0, v59
	s_nop 1
	v_cndmask_b32_e32 v59, 1.0, v70, vcc
	v_div_scale_f32 v70, s[24:25], v59, v59, 1.0
	v_rcp_f32_e32 v71, v70
	v_div_scale_f32 v72, vcc, 1.0, v59, 1.0
	v_fma_f32 v73, -v70, v71, 1.0
; __device__ __forceinline__ void xn2_rows(const bf16* __restrict__ hb, const float* __restrict__ g, bf16* __restrict__ outp, unsigned char* __restrict__ xq, float* __restrict__ xs, int gwave, int nwaves, int lane, int rend) {
;     ...
;         const v4u* xb = (const v4u*)(hb + (size_t)row * D) + lane;
;         float v[2][8]; float ss = 0.f;
; #pragma unroll
;         for (int j = 0; j < 2; ++j) { const v4u w = xb[64 * j]; const unsigned ww[4] = {w.x, w.y, w.z, w.w};
; #pragma unroll
;             for (int e = 0; e < 4; ++e) { v[j][2 * e] = __uint_as_float(ww[e] << 16); v[j][2 * e + 1] = __uint_as_float(ww[e] & 0xffff0000u); ss += v[j][2 * e] * v[j][2 * e] + v[j][2 * e + 1] * v[j][2 * e + 1]; } }
;         ss = wave_sum(ss);
;         const float r = rsqrtf(ss * (1.f / D) + EPS);
;         float y[2][8]; float mx = 0.f;
; #pragma unroll
;         for (int j = 0; j < 2; ++j) { const float4 g0 = ((const float4*)g)[2 * lane + 128 * j], g1 = ((const float4*)g)[2 * lane + 128 * j + 1]; const float gg[8] = {g0.x, g0.y, g0.z, g0.w, g1.x, g1.y, g1.z, g1.w};
; #pragma unroll
;             for (int e = 0; e < 8; ++e) { y[j][e] = v[j][e] * r * gg[e]; mx = fmaxf(mx, fabsf(y[j][e])); }
;             v4u ow; ow.x = pk2(y[j][0], y[j][1]); ow.y = pk2(y[j][2], y[j][3]); ow.z = pk2(y[j][4], y[j][5]); ow.w = pk2(y[j][6], y[j][7]);
;             __builtin_amdgcn_raw_buffer_store_b128(ow, rsO, (int)(((unsigned)row * D + 8u * (unsigned)lane + 512u * j) * 2u), 0, 16); }
;         mx = wave_max_dpp(mx);
;         const float sc = mx > 0.f ? mx * (1.f / 119.f) : 1.f, inv = 1.f / sc;
;         int sx = 0; unsigned W[4];
; #pragma unroll
;         for (int j = 0; j < 2; ++j) { unsigned wh = 0u, wl = 0u;
; #pragma unroll
;             for (int e = 0; e < 8; ++e) { const int q = (int)rintf(y[j][e] * inv); sx += q; const unsigned tq = (unsigned)(q + 8);
;                 wl |= ((tq & 15u) ^ 8u) << (4 * e); wh |= (((unsigned)((int)tq >> 4)) & 15u) << (4 * e); }
;             W[j] = wh; W[2 + j] = wl; }
;         { const bool o1 = (lane & 1) != 0, o2 = (lane & 2) != 0;
; #pragma unroll
;           for (int p = 0; p < 4; p += 2) { const unsigned t = o1 ? W[p] : W[p + 1]; const unsigned rc = (unsigned)__builtin_amdgcn_update_dpp(0, (int)t, 0xB1, 0xf, 0xf, false); if (o1) W[p] = rc; else W[p + 1] = rc; }
; #pragma unroll
	v_fmac_f32_e32 v71, v73, v71
	v_mul_f32_e32 v73, v72, v71
	v_fma_f32 v74, -v70, v73, v72
	v_fmac_f32_e32 v73, v74, v71
	v_fma_f32 v70, -v70, v73, v72
	v_div_fmas_f32 v70, v70, v71, v73
	v_div_fixup_f32 v60, v70, v59, 1.0
	v_pk_mul_f32 v[56:57], v[60:61], v[164:165] op_sel_hi:[0,1]
	v_pk_add_f32 v[180:181], s[46:47], v[56:57]
	v_pk_mul_f32 v[56:57], v[60:61], v[166:167] op_sel_hi:[0,1]
	v_pk_add_f32 v[182:183], s[46:47], v[56:57]
	v_pk_mul_f32 v[56:57], v[60:61], v[168:169] op_sel_hi:[0,1]
	v_pk_add_f32 v[184:185], s[46:47], v[56:57]
	v_pk_mul_f32 v[56:57], v[60:61], v[170:171] op_sel_hi:[0,1]
	v_pk_add_f32 v[186:187], s[46:47], v[56:57]
	v_pk_mul_f32 v[56:57], v[60:61], v[172:173] op_sel_hi:[0,1]
	v_pk_add_f32 v[188:189], s[46:47], v[56:57]
	v_pk_mul_f32 v[56:57], v[60:61], v[174:175] op_sel_hi:[0,1]
	v_pk_add_f32 v[190:191], s[46:47], v[56:57]
	v_pk_mul_f32 v[56:57], v[60:61], v[176:177] op_sel_hi:[0,1]
	v_pk_add_f32 v[192:193], s[46:47], v[56:57]
	v_pk_mul_f32 v[56:57], v[60:61], v[178:179] op_sel_hi:[0,1]
	v_pk_add_f32 v[194:195], s[46:47], v[56:57]
	v_add3_u32 v208, v180, v181, v182
	v_add3_u32 v208, v208, v183, v184
	v_add3_u32 v208, v208, v185, v186
	v_add3_u32 v208, v208, v187, v188
	v_add3_u32 v208, v208, v189, v190
	v_add3_u32 v208, v208, v191, v192
	v_add3_u32 v208, v208, v193, v194
	v_add_u32_e32 v208, v208, v195
	v_add_u32_e32 v208, 0x4bffff80, v208
	v_perm_b32 v204, v182, v180, s48
	v_perm_b32 v205, v186, v184, s48
	v_perm_b32 v196, v205, v204, s49
	v_perm_b32 v204, v183, v181, s48
	v_perm_b32 v205, v187, v185, s48
	v_perm_b32 v197, v205, v204, s49
	v_lshlrev_b32_e32 v204, 4, v197
	v_lshrrev_b32_e32 v205, 4, v196
	v_bfi_b32 v202, s45, v196, v204
	v_bfi_b32 v200, s45, v205, v197
	v_xor_b32_e32 v202, 0x88888888, v202
	v_perm_b32 v204, v190, v188, s48
	v_perm_b32 v205, v194, v192, s48
	v_perm_b32 v196, v205, v204, s49
	v_perm_b32 v204, v191, v189, s48
	v_perm_b32 v205, v195, v193, s48
	v_perm_b32 v197, v205, v204, s49
	v_lshlrev_b32_e32 v204, 4, v197
	v_lshrrev_b32_e32 v205, 4, v196
	v_bfi_b32 v203, s45, v196, v204
	v_bfi_b32 v201, s45, v205, v197
	v_xor_b32_e32 v203, 0x88888888, v203
	v_cndmask_b32_e64 v204, v200, v201, s[4:5]
	v_cndmask_b32_e64 v205, v202, v203, s[4:5]
	s_nop 1
	v_mov_b32_dpp v206, v204 quad_perm:[1,0,3,2] row_mask:0xf bank_mask:0xf
	v_mov_b32_dpp v207, v205 quad_perm:[1,0,3,2] row_mask:0xf bank_mask:0xf
	s_nop 0
	v_cndmask_b32_e64 v200, v206, v200, s[4:5]
	v_cndmask_b32_e64 v201, v201, v206, s[4:5]
	v_cndmask_b32_e64 v202, v207, v202, s[4:5]
	v_cndmask_b32_e64 v203, v203, v207, s[4:5]
	v_cndmask_b32_e64 v204, v200, v202, s[6:7]
	v_cndmask_b32_e64 v205, v201, v203, s[6:7]
	s_nop 1
	v_mov_b32_dpp v206, v204 quad_perm:[2,3,0,1] row_mask:0xf bank_mask:0xf
	v_mov_b32_dpp v207, v205 quad_perm:[2,3,0,1] row_mask:0xf bank_mask:0xf
	s_nop 0
	v_cndmask_b32_e64 v200, v206, v200, s[6:7]
	v_cndmask_b32_e64 v202, v202, v206, s[6:7]
	v_cndmask_b32_e64 v201, v207, v201, s[6:7]
	v_cndmask_b32_e64 v203, v203, v207, s[6:7]
	buffer_store_dwordx4 v[200:203], v211, s[16:19], 0 offen sc1
	v_add_u32_e32 v211, 0x1000, v211
	s_nop 1
	v_add_u32_dpp v208, v208, v208 quad_perm:[1,0,3,2] row_mask:0xf bank_mask:0xf bound_ctrl:1
	s_nop 1
	v_add_u32_dpp v208, v208, v208 quad_perm:[2,3,0,1] row_mask:0xf bank_mask:0xf bound_ctrl:1
	s_nop 1
	v_add_u32_dpp v208, v208, v208 row_half_mirror row_mask:0xf bank_mask:0xf bound_ctrl:1
	s_nop 1
	v_add_u32_dpp v208, v208, v208 row_mirror row_mask:0xf bank_mask:0xf bound_ctrl:1
	s_nop 1
	v_readlane_b32 s28, v208, 0
	v_readlane_b32 s29, v208, 16
	v_readlane_b32 s30, v208, 32
	v_readlane_b32 s31, v208, 48
	s_nop 1
	s_add_i32 s28, s29, s28
	s_add_i32 s28, s28, s30
	s_add_i32 s30, s28, s31
	s_and_saveexec_b64 s[24:25], s[8:9]
	v_mov_b32_e32 v70, s98
	v_mov_b32_e32 v71, s30
	ds_write_b32 v70, v59
	ds_write_b32 v70, v71 offset:256
	s_mov_b64 exec, s[24:25]
	s_add_i32 s98, s98, 32
	s_waitcnt vmcnt(8)
	v_lshlrev_b32_e32 v34, 16, v92
	v_and_b32_e32 v35, 0xffff0000, v92
	v_lshlrev_b32_e32 v36, 16, v93
	v_and_b32_e32 v37, 0xffff0000, v93
	v_lshlrev_b32_e32 v38, 16, v94
	v_and_b32_e32 v39, 0xffff0000, v94
	v_lshlrev_b32_e32 v40, 16, v95
	v_and_b32_e32 v41, 0xffff0000, v95
	v_lshlrev_b32_e32 v42, 16, v96
	v_and_b32_e32 v43, 0xffff0000, v96
	v_lshlrev_b32_e32 v44, 16, v97
	v_and_b32_e32 v45, 0xffff0000, v97
	v_lshlrev_b32_e32 v46, 16, v98
	v_and_b32_e32 v47, 0xffff0000, v98
	v_lshlrev_b32_e32 v48, 16, v99
	v_and_b32_e32 v49, 0xffff0000, v99
	v_lshl_add_u64 v[150:151], v[150:151], 0, s[100:101]
	global_load_dwordx4 v[92:95], v[150:151], off
	global_load_dwordx4 v[96:99], v[150:151], off offset:1024
	v_pk_mul_f32 v[50:51], v[34:35], v[34:35]
	v_pk_fma_f32 v[50:51], v[36:37], v[36:37], v[50:51]
	v_pk_fma_f32 v[50:51], v[38:39], v[38:39], v[50:51]
	v_pk_fma_f32 v[50:51], v[40:41], v[40:41], v[50:51]
	v_pk_fma_f32 v[50:51], v[42:43], v[42:43], v[50:51]
	v_pk_fma_f32 v[50:51], v[44:45], v[44:45], v[50:51]
	v_pk_fma_f32 v[50:51], v[46:47], v[46:47], v[50:51]
	v_pk_fma_f32 v[50:51], v[48:49], v[48:49], v[50:51]
	v_add_f32_e32 v52, v50, v51
	s_nop 1
	v_add_f32_dpp v52, v52, v52 quad_perm:[1,0,3,2] row_mask:0xf bank_mask:0xf bound_ctrl:1
	s_nop 1
	v_add_f32_dpp v52, v52, v52 quad_perm:[2,3,0,1] row_mask:0xf bank_mask:0xf bound_ctrl:1
	s_nop 1
	v_add_f32_dpp v52, v52, v52 row_half_mirror row_mask:0xf bank_mask:0xf bound_ctrl:1
	s_nop 1
	v_add_f32_dpp v52, v52, v52 row_mirror row_mask:0xf bank_mask:0xf bound_ctrl:1
	s_nop 1
	v_readlane_b32 s28, v52, 16
	v_readlane_b32 s29, v52, 48
	v_readlane_b32 s24, v52, 0
	v_readlane_b32 s25, v52, 32
	s_nop 1
	v_mov_b32_e32 v52, s28
	v_mov_b32_e32 v53, s29
	v_pk_add_f32 v[52:53], s[24:25], v[52:53]
; __device__ __forceinline__ void xn2_rows(const bf16* __restrict__ hb, const float* __restrict__ g, bf16* __restrict__ outp, unsigned char* __restrict__ xq, float* __restrict__ xs, int gwave, int nwaves, int lane, int rend) {
;     ...
;         const float r = rsqrtf(ss * (1.f / D) + EPS);
;         float y[2][8]; float mx = 0.f;
; #pragma unroll
;         for (int j = 0; j < 2; ++j) { const float4 g0 = ((const float4*)g)[2 * lane + 128 * j], g1 = ((const float4*)g)[2 * lane + 128 * j + 1]; const float gg[8] = {g0.x, g0.y, g0.z, g0.w, g1.x, g1.y, g1.z, g1.w};
; #pragma unroll
;             for (int e = 0; e < 8; ++e) { y[j][e] = v[j][e] * r * gg[e]; mx = fmaxf(mx, fabsf(y[j][e])); }
;             v4u ow; ow.x = pk2(y[j][0], y[j][1]); ow.y = pk2(y[j][2], y[j][3]); ow.z = pk2(y[j][4], y[j][5]); ow.w = pk2(y[j][6], y[j][7]);
;             __builtin_amdgcn_raw_buffer_store_b128(ow, rsO, (int)(((unsigned)row * D + 8u * (unsigned)lane + 512u * j) * 2u), 0, 16); }
;         mx = wave_max_dpp(mx);
;         const float sc = mx > 0.f ? mx * (1.f / 119.f) : 1.f, inv = 1.f / sc;
;         int sx = 0; unsigned W[4];
; #pragma unroll
;         for (int j = 0; j < 2; ++j) { unsigned wh = 0u, wl = 0u;
; #pragma unroll
;             for (int e = 0; e < 8; ++e) { const int q = (int)rintf(y[j][e] * inv); sx += q; const unsigned tq = (unsigned)(q + 8);
;                 wl |= ((tq & 15u) ^ 8u) << (4 * e); wh |= (((unsigned)((int)tq >> 4)) & 15u) << (4 * e); }
;             W[j] = wh; W[2 + j] = wl; }
;         { const bool o1 = (lane & 1) != 0, o2 = (lane & 2) != 0;
; #pragma unroll
;           for (int p = 0; p < 4; p += 2) { const unsigned t = o1 ? W[p] : W[p + 1]; const unsigned rc = (unsigned)__builtin_amdgcn_update_dpp(0, (int)t, 0xB1, 0xf, 0xf, false); if (o1) W[p] = rc; else W[p + 1] = rc; }
; #pragma unroll
;           for (int p = 0; p < 2; ++p) { const unsigned t = o2 ? W[p] : W[p + 2]; const unsigned rc = (unsigned)__builtin_amdgcn_update_dpp(0, (int)t, 0x4E, 0xf, 0xf, false); if (o2) W[p] = rc; else W[p + 2] = rc; } }
;         { const int m = lane & 3; v4u pw; pw.x = W[0]; pw.y = W[1]; pw.z = W[2]; pw.w = W[3];
;           __builtin_amdgcn_raw_buffer_store_b128(pw, rsQ, (int)((m & 2 ? 8u * (unsigned)MiB : 0u) + (unsigned)row * 512u + (unsigned)(m & 1) * 256u + 16u * (unsigned)(lane >> 2)), 0, 16); }
;         sx = wave_sum_dpp_i(sx);
	s_nop 0
	v_add_f32_e32 v52, v52, v53
	v_fmamk_f32 v52, v52, 0x3a800000, v29
	v_rsq_f32_e32 v54, v52
	s_nop 0
	v_pk_mul_f32 v[56:57], v[54:55], v[34:35] op_sel_hi:[0,1]
	v_pk_mul_f32 v[164:165], v[6:7], v[56:57]
	v_pk_mul_f32 v[56:57], v[54:55], v[36:37] op_sel_hi:[0,1]
	v_pk_mul_f32 v[166:167], v[8:9], v[56:57]
	v_pk_mul_f32 v[56:57], v[54:55], v[38:39] op_sel_hi:[0,1]
	v_pk_mul_f32 v[168:169], v[2:3], v[56:57]
	v_pk_mul_f32 v[56:57], v[54:55], v[40:41] op_sel_hi:[0,1]
	v_pk_mul_f32 v[170:171], v[4:5], v[56:57]
	v_pk_mul_f32 v[56:57], v[54:55], v[42:43] op_sel_hi:[0,1]
	v_pk_mul_f32 v[172:173], v[14:15], v[56:57]
	v_pk_mul_f32 v[56:57], v[54:55], v[44:45] op_sel_hi:[0,1]
	v_pk_mul_f32 v[174:175], v[16:17], v[56:57]
	v_pk_mul_f32 v[56:57], v[54:55], v[46:47] op_sel_hi:[0,1]
	v_pk_mul_f32 v[176:177], v[10:11], v[56:57]
	v_pk_mul_f32 v[56:57], v[54:55], v[48:49] op_sel_hi:[0,1]
	v_pk_mul_f32 v[178:179], v[12:13], v[56:57]
	v_max3_f32 v58, |v164|, 0, |v165|
	v_max3_f32 v58, v58, |v166|, |v167|
	v_max3_f32 v58, v58, |v168|, |v169|
	v_max3_f32 v58, v58, |v170|, |v171|
	v_max3_f32 v58, v58, |v172|, |v173|
	v_max3_f32 v58, v58, |v174|, |v175|
	v_max3_f32 v58, v58, |v176|, |v177|
	v_max3_f32 v58, v58, |v178|, |v179|
	v_cvt_pk_bf16_f32 v62, v164, v165
	v_cvt_pk_bf16_f32 v63, v166, v167
	v_cvt_pk_bf16_f32 v64, v168, v169
	v_cvt_pk_bf16_f32 v65, v170, v171
	v_cvt_pk_bf16_f32 v66, v172, v173
	v_cvt_pk_bf16_f32 v67, v174, v175
	v_cvt_pk_bf16_f32 v68, v176, v177
	v_cvt_pk_bf16_f32 v69, v178, v179
	buffer_store_dwordx4 v[62:65], v210, s[12:15], 0 offen sc1
	buffer_store_dwordx4 v[66:69], v210, s[12:15], 0 offen offset:1024 sc1
	v_add_u32_e32 v210, 0x4000, v210
	s_nop 1
	v_max_f32_dpp v58, v58, v58 quad_perm:[1,0,3,2] row_mask:0xf bank_mask:0xf
	s_nop 1
	v_max_f32_dpp v58, v58, v58 quad_perm:[2,3,0,1] row_mask:0xf bank_mask:0xf
	s_nop 1
	v_max_f32_dpp v58, v58, v58 row_half_mirror row_mask:0xf bank_mask:0xf
	s_nop 1
	v_max_f32_dpp v58, v58, v58 row_mirror row_mask:0xf bank_mask:0xf
	s_nop 1
	v_readlane_b32 s28, v58, 32
	v_readlane_b32 s29, v58, 48
	v_readlane_b32 s24, v58, 0
	v_readlane_b32 s25, v58, 16
	s_nop 1
	v_mov_b32_e32 v59, s29
	v_max_f32_e32 v59, s28, v59
	v_mov_b32_e32 v70, s25
	v_max3_f32 v59, s24, v70, v59
	v_mul_f32_e32 v70, 0x3c09ae41, v59
	v_cmp_lt_f32_e32 vcc, 0, v59
	s_nop 1
	v_cndmask_b32_e32 v59, 1.0, v70, vcc
	v_div_scale_f32 v70, s[24:25], v59, v59, 1.0
	v_rcp_f32_e32 v71, v70
	v_div_scale_f32 v72, vcc, 1.0, v59, 1.0
	v_fma_f32 v73, -v70, v71, 1.0
	v_fmac_f32_e32 v71, v73, v71
	v_mul_f32_e32 v73, v72, v71
	v_fma_f32 v74, -v70, v73, v72
	v_fmac_f32_e32 v73, v74, v71
	v_fma_f32 v70, -v70, v73, v72
	v_div_fmas_f32 v70, v70, v71, v73
	v_div_fixup_f32 v60, v70, v59, 1.0
	v_pk_mul_f32 v[56:57], v[60:61], v[164:165] op_sel_hi:[0,1]
	v_pk_add_f32 v[180:181], s[46:47], v[56:57]
	v_pk_mul_f32 v[56:57], v[60:61], v[166:167] op_sel_hi:[0,1]
	v_pk_add_f32 v[182:183], s[46:47], v[56:57]
	v_pk_mul_f32 v[56:57], v[60:61], v[168:169] op_sel_hi:[0,1]
	v_pk_add_f32 v[184:185], s[46:47], v[56:57]
	v_pk_mul_f32 v[56:57], v[60:61], v[170:171] op_sel_hi:[0,1]
	v_pk_add_f32 v[186:187], s[46:47], v[56:57]
	v_pk_mul_f32 v[56:57], v[60:61], v[172:173] op_sel_hi:[0,1]
	v_pk_add_f32 v[188:189], s[46:47], v[56:57]
	v_pk_mul_f32 v[56:57], v[60:61], v[174:175] op_sel_hi:[0,1]
	v_pk_add_f32 v[190:191], s[46:47], v[56:57]
	v_pk_mul_f32 v[56:57], v[60:61], v[176:177] op_sel_hi:[0,1]
	v_pk_add_f32 v[192:193], s[46:47], v[56:57]
	v_pk_mul_f32 v[56:57], v[60:61], v[178:179] op_sel_hi:[0,1]
	v_pk_add_f32 v[194:195], s[46:47], v[56:57]
	v_add3_u32 v208, v180, v181, v182
	v_add3_u32 v208, v208, v183, v184
	v_add3_u32 v208, v208, v185, v186
	v_add3_u32 v208, v208, v187, v188
	v_add3_u32 v208, v208, v189, v190
	v_add3_u32 v208, v208, v191, v192
	v_add3_u32 v208, v208, v193, v194
	v_add_u32_e32 v208, v208, v195
	v_add_u32_e32 v208, 0x4bffff80, v208
	v_perm_b32 v204, v182, v180, s48
	v_perm_b32 v205, v186, v184, s48
	v_perm_b32 v196, v205, v204, s49
	v_perm_b32 v204, v183, v181, s48
	v_perm_b32 v205, v187, v185, s48
	v_perm_b32 v197, v205, v204, s49
	v_lshlrev_b32_e32 v204, 4, v197
	v_lshrrev_b32_e32 v205, 4, v196
	v_bfi_b32 v202, s45, v196, v204
	v_bfi_b32 v200, s45, v205, v197
	v_xor_b32_e32 v202, 0x88888888, v202
	v_perm_b32 v204, v190, v188, s48
	v_perm_b32 v205, v194, v192, s48
	v_perm_b32 v196, v205, v204, s49
	v_perm_b32 v204, v191, v189, s48
	v_perm_b32 v205, v195, v193, s48
	v_perm_b32 v197, v205, v204, s49
	v_lshlrev_b32_e32 v204, 4, v197
	v_lshrrev_b32_e32 v205, 4, v196
	v_bfi_b32 v203, s45, v196, v204
	v_bfi_b32 v201, s45, v205, v197
	v_xor_b32_e32 v203, 0x88888888, v203
	v_cndmask_b32_e64 v204, v200, v201, s[4:5]
	v_cndmask_b32_e64 v205, v202, v203, s[4:5]
	s_nop 1
	v_mov_b32_dpp v206, v204 quad_perm:[1,0,3,2] row_mask:0xf bank_mask:0xf
	v_mov_b32_dpp v207, v205 quad_perm:[1,0,3,2] row_mask:0xf bank_mask:0xf
	s_nop 0
	v_cndmask_b32_e64 v200, v206, v200, s[4:5]
	v_cndmask_b32_e64 v201, v201, v206, s[4:5]
	v_cndmask_b32_e64 v202, v207, v202, s[4:5]
	v_cndmask_b32_e64 v203, v203, v207, s[4:5]
	v_cndmask_b32_e64 v204, v200, v202, s[6:7]
	v_cndmask_b32_e64 v205, v201, v203, s[6:7]
	s_nop 1
	v_mov_b32_dpp v206, v204 quad_perm:[2,3,0,1] row_mask:0xf bank_mask:0xf
	v_mov_b32_dpp v207, v205 quad_perm:[2,3,0,1] row_mask:0xf bank_mask:0xf
	s_nop 0
	v_cndmask_b32_e64 v200, v206, v200, s[6:7]
	v_cndmask_b32_e64 v202, v202, v206, s[6:7]
	v_cndmask_b32_e64 v201, v207, v201, s[6:7]
	v_cndmask_b32_e64 v203, v203, v207, s[6:7]
	buffer_store_dwordx4 v[200:203], v211, s[16:19], 0 offen sc1
	v_add_u32_e32 v211, 0x1000, v211
	s_nop 1
	v_add_u32_dpp v208, v208, v208 quad_perm:[1,0,3,2] row_mask:0xf bank_mask:0xf bound_ctrl:1
	s_nop 1
	v_add_u32_dpp v208, v208, v208 quad_perm:[2,3,0,1] row_mask:0xf bank_mask:0xf bound_ctrl:1
	s_nop 1
	v_add_u32_dpp v208, v208, v208 row_half_mirror row_mask:0xf bank_mask:0xf bound_ctrl:1
	s_nop 1
	v_add_u32_dpp v208, v208, v208 row_mirror row_mask:0xf bank_mask:0xf bound_ctrl:1
	s_nop 1
	v_readlane_b32 s28, v208, 0
	v_readlane_b32 s29, v208, 16
	v_readlane_b32 s30, v208, 32
	v_readlane_b32 s31, v208, 48
	s_nop 1
	s_add_i32 s28, s29, s28
	s_add_i32 s28, s28, s30
	s_add_i32 s30, s28, s31
	s_and_saveexec_b64 s[24:25], s[8:9]
	v_mov_b32_e32 v70, s98
	v_mov_b32_e32 v71, s30
	ds_write_b32 v70, v59
	ds_write_b32 v70, v71 offset:256
	s_mov_b64 exec, s[24:25]
	s_add_i32 s98, s98, 32
	s_add_i32 s32, s32, 1
	s_cmp_eq_u32 s32, 3
	s_cselect_b32 s100, 0, s100
	s_cmp_lg_u32 s32, 4
	s_cbranch_scc1 .Lp8_trip
	s_waitcnt lgkmcnt(0)
	s_barrier
	s_cmp_lg_u32 s95, 0
	s_cbranch_scc1 .Lp8_xs_done
	v_lshrrev_b32_e32 v70, 2, v18
	ds_read_b32 v71, v70
	ds_read_b32 v72, v70 offset:256
	s_lshl_b32 s10, s42, 6
	s_lshl_b32 s11, s43, 8
	s_add_i32 s24, s10, s11
	s_lshl_b32 s24, s24, 2
	s_add_u32 s28, s90, s24
	s_addc_u32 s29, s91, 0
	v_add_u32_e32 v73, v30, v70
	v_add_u32_e32 v74, v31, v70
	s_waitcnt lgkmcnt(0)
	global_store_dword v73, v71, s[28:29] sc1
	global_store_dword v74, v72, s[28:29] sc1
; __device__ __forceinline__ unsigned xb_add(unsigned* p, unsigned v) { return __hip_atomic_fetch_add(p, v, __ATOMIC_RELAXED, __HIP_MEMORY_SCOPE_AGENT); }
; __global__ void __launch_bounds__(NTHR, 2) k_main(Args a) {
;     ...
;             xn2_rows(HB, a.norm_ffn_g, XNB, XQ, XS, r0 + wave, 8, lane, r0 + 64);
;             asm volatile("s_waitcnt vmcnt(0)" ::: "memory");
;             __syncthreads();
;             if (tid == 0) (void)xb_add(&((unsigned*)ws)[6144 + 16 * u.pm], 1u);
;         }
.Lp8_xs_done:
.LBB0_569:
	s_waitcnt vmcnt(0)
	s_barrier
	s_and_saveexec_b64 s[10:11], s[0:1]
	s_cbranch_execz .LBB0_540
	s_mov_b64 s[24:25], exec
	v_mbcnt_lo_u32_b32 v2, s24, 0
	v_mbcnt_hi_u32_b32 v2, s25, v2
	v_cmp_eq_u32_e32 vcc, 0, v2
	s_and_b64 s[26:27], exec, vcc
	s_mov_b64 exec, s[26:27]
	s_cbranch_execz .LBB0_540
	s_lshl_b32 s26, s43, 4
	s_ashr_i32 s27, s26, 31
	s_lshl_b64 s[26:27], s[26:27], 2
	s_add_u32 s26, s90, s26
	s_addc_u32 s27, s91, s27
	s_bcnt1_i32_b64 s24, s[24:25]
	v_mov_b32_e32 v2, s24
	global_atomic_add v32, v2, s[26:27]
	s_branch .LBB0_540
